# dt_phase: WdtT staged once per workgroup into swizzled LDS, B fragments via ds_read_b128, A loads pipelined in 8 batches (fully unrolled 64 k-steps)
# speedup vs baseline: 1.0105x; 1.0051x over previous
; __device__ __forceinline__ void dt_phase(const Ptrs& P, int gw, int NGW, int lane) {
;     const bf16_t* U = (const bf16_t*)(P.ws + WS_U); const bf16_t* WdtT = (const bf16_t*)((unsigned char*)P.out + DO_WDT); float* dtraw = (float*)((unsigned char*)P.out + DO_DTRAW);
;     const int lc = lane & 15, g = lane >> 4;
;     for (int it = gw; it < MTOK / 16; it += NGW) {
;         const int r0 = 16 * it; f32x4 acc = {0.f, 0.f, 0.f, 0.f};
;         const bf16_t* ap = U + (size_t)(r0 + lc) * DM + 8 * g; const bf16_t* bp = WdtT + (size_t)lc * DM + 8 * g;
.LBB0_230:
	s_getreg_b32 s3, hwreg(HW_REG_HW_ID, 0, 6)
	s_and_b32 s3, s3, 63
	s_lshl_b32 s3, s3, 2
	s_add_i32 s3, s3, 0
	s_add_i32 s3, s3, 0x27ef0
	v_mov_b32_e32 v0, s3
	ds_read_b32 v0, v0
	s_mov_b64 s[6:7], s[0:1]
	s_waitcnt lgkmcnt(0)
	v_readfirstlane_b32 s3, v0
	s_nop 1
	v_lshl_add_u32 v1, s3, 6, v213
	v_readlane_b32 s3, v255, 18
	v_ashrrev_i32_e32 v0, 6, v1
	s_nop 0
	v_add_u32_e32 v14, s3, v0
	s_movk_i32 s3, 0x802
	v_cmp_gt_i32_e32 vcc, s3, v14
	s_and_saveexec_b64 s[4:5], vcc
	s_xor_b64 s[4:5], exec, s[4:5]
	s_cbranch_execz .LBB0_236
	global_load_dwordx4 v[8:11], v16, s[6:7] offset:176
	v_and_b32_e32 v5, 15, v1
	v_bfe_u32 v2, v1, 4, 2
	v_mov_b32_e32 v1, v16
	v_lshlrev_b32_e32 v4, 4, v0
	v_lshlrev_b32_e32 v15, 2, v2
	v_lshlrev_b32_e32 v0, 2, v5
	v_lshlrev_b32_e32 v2, 4, v2
	v_mov_b32_e32 v3, v16
	v_mov_b32_e32 v13, v16
	v_readlane_b32 s3, v255, 20
	v_lshl_or_b32 v12, v5, 12, v2
	s_mov_b64 s[6:7], 0xd300000
	v_add3_u32 v4, s3, v4, v5
	s_waitcnt vmcnt(0)
	v_lshl_add_u64 v[0:1], v[8:9], 0, v[0:1]
	v_lshl_add_u64 v[6:7], v[10:11], 0, v[2:3]
	v_lshl_add_u64 v[8:9], v[8:9], 0, v[12:13]
	v_lshl_add_u64 v[10:11], v[0:1], 0, s[6:7]
	s_mov_b64 s[6:7], 0
	s_load_dwordx2 s[100:101], s[0:1], 0xb0
	v_and_b32_e32 v17, 15, v213
	v_lshrrev_b32_e32 v62, 4, v213
	v_and_b32_e32 v70, 3, v17
	v_xor_b32_e32 v70, v70, v62
	v_lshrrev_b32_e32 v72, 2, v17
	v_xor_b32_e32 v73, 0, v72
	v_lshl_or_b32 v73, v73, 2, v70
	v_lshlrev_b32_e32 v73, 4, v73
	v_lshl_add_u32 v73, v17, 12, v73
	v_xor_b32_e32 v90, 1, v72
	v_lshl_or_b32 v90, v90, 2, v70
	v_lshlrev_b32_e32 v90, 4, v90
	v_lshl_add_u32 v90, v17, 12, v90
	v_xor_b32_e32 v91, 2, v72
	v_lshl_or_b32 v91, v91, 2, v70
	v_lshlrev_b32_e32 v91, 4, v91
	v_lshl_add_u32 v91, v17, 12, v91
	v_xor_b32_e32 v124, 3, v72
	v_lshl_or_b32 v124, v124, 2, v70
	v_lshlrev_b32_e32 v124, 4, v124
	v_lshl_add_u32 v124, v17, 12, v124
	v_and_b32_e32 v125, 7, v14
	v_lshlrev_b32_e32 v125, 1, v125
	s_waitcnt lgkmcnt(0)
	s_add_u32 s100, s100, 0x8f00000
	s_addc_u32 s101, s101, 0
	v_xor_b32_e32 v192, v125, v213
	v_lshlrev_b32_e32 v192, 4, v192
	v_lshl_add_u32 v192, v125, 12, v192
	global_load_dwordx4 v[76:79], v192, s[100:101]
	global_load_dwordx4 v[80:83], v192, s[100:101] offset:1024
	global_load_dwordx4 v[84:87], v192, s[100:101] offset:2048
	global_load_dwordx4 v[92:95], v192, s[100:101] offset:3072
	v_add_u32_e32 v125, 1, v125
	v_xor_b32_e32 v192, v125, v213
	v_lshlrev_b32_e32 v192, 4, v192
	v_lshl_add_u32 v192, v125, 12, v192
	global_load_dwordx4 v[96:99], v192, s[100:101]
	global_load_dwordx4 v[100:103], v192, s[100:101] offset:1024
	global_load_dwordx4 v[104:107], v192, s[100:101] offset:2048
	global_load_dwordx4 v[112:115], v192, s[100:101] offset:3072
	s_waitcnt vmcnt(0)
	v_lshlrev_b32_e32 v193, 4, v213
	v_add_u32_e32 v192, -1, v125
	v_lshl_add_u32 v193, v192, 12, v193
	ds_write_b128 v193, v[76:79]
	ds_write_b128 v193, v[80:83] offset:1024
	ds_write_b128 v193, v[84:87] offset:2048
	ds_write_b128 v193, v[92:95] offset:3072
	v_lshlrev_b32_e32 v193, 4, v213
	v_add_u32_e32 v192, 0, v125
	v_lshl_add_u32 v193, v192, 12, v193
	ds_write_b128 v193, v[96:99]
	ds_write_b128 v193, v[100:103] offset:1024
	ds_write_b128 v193, v[104:107] offset:2048
	ds_write_b128 v193, v[112:115] offset:3072
	s_waitcnt lgkmcnt(0)
	s_barrier

; __device__ __forceinline__ f32x4 mfma32(bf16x8 a, bf16x8 b, f32x4 c) { return __builtin_amdgcn_mfma_f32_16x16x32_bf16(a, b, c, 0, 0, 0); }
; __device__ __forceinline__ void dt_phase(const Ptrs& P, int gw, int NGW, int lane) {
;     ...
;     for (int it = gw; it < MTOK / 16; it += NGW) {
;         const int r0 = 16 * it; f32x4 acc = {0.f, 0.f, 0.f, 0.f};
;         const bf16_t* ap = U + (size_t)(r0 + lc) * DM + 8 * g; const bf16_t* bp = WdtT + (size_t)lc * DM + 8 * g;
; #pragma unroll 8
;         for (int ks = 0; ks < 64; ++ks) { const bf16x8 a = *(const bf16x8*)(ap + ks * 32); const bf16x8 b = *(const bf16x8*)(bp + ks * 32); acc = mfma32(a, b, acc); }
; #pragma unroll
;         for (int r = 0; r < 4; ++r) dtraw[(size_t)(r0 + 4 * g + r) * 16 + lc] = acc[r];
;     }
.LBB0_233:
	s_mov_b64 s[100:101], 0x10300000
	v_lshl_add_u64 v[214:215], v[12:13], 0, s[100:101]
	global_load_dwordx4 v[76:79], v[214:215], off
	ds_read_b128 v[152:155], v73
	global_load_dwordx4 v[80:83], v[214:215], off offset:64
	ds_read_b128 v[156:159], v90
	global_load_dwordx4 v[84:87], v[214:215], off offset:128
	ds_read_b128 v[160:163], v91
	global_load_dwordx4 v[92:95], v[214:215], off offset:192
	ds_read_b128 v[164:167], v124
	global_load_dwordx4 v[96:99], v[214:215], off offset:256
	ds_read_b128 v[168:171], v73 offset:256
	global_load_dwordx4 v[100:103], v[214:215], off offset:320
	ds_read_b128 v[172:175], v90 offset:256
	global_load_dwordx4 v[104:107], v[214:215], off offset:384
	ds_read_b128 v[176:179], v91 offset:256
	global_load_dwordx4 v[112:115], v[214:215], off offset:448
	ds_read_b128 v[180:183], v124 offset:256
	global_load_dwordx4 v[116:119], v[214:215], off offset:512
	ds_read_b128 v[184:187], v73 offset:512
	global_load_dwordx4 v[120:123], v[214:215], off offset:576
	ds_read_b128 v[188:191], v90 offset:512
	global_load_dwordx4 v[128:131], v[214:215], off offset:640
	ds_read_b128 v[196:199], v91 offset:512
	global_load_dwordx4 v[132:135], v[214:215], off offset:704
	ds_read_b128 v[200:203], v124 offset:512
	global_load_dwordx4 v[136:139], v[214:215], off offset:768
	ds_read_b128 v[204:207], v73 offset:768
	global_load_dwordx4 v[140:143], v[214:215], off offset:832
	ds_read_b128 v[208:211], v90 offset:768
	global_load_dwordx4 v[144:147], v[214:215], off offset:896
	ds_read_b128 v[216:219], v91 offset:768
	global_load_dwordx4 v[148:151], v[214:215], off offset:960
	ds_read_b128 v[220:223], v124 offset:768
	s_waitcnt vmcnt(15) lgkmcnt(15)
	v_mfma_f32_16x16x32_bf16 v[0:3], v[76:79], v[152:155], v[0:3]
	s_waitcnt vmcnt(14) lgkmcnt(14)
	v_mfma_f32_16x16x32_bf16 v[0:3], v[80:83], v[156:159], v[0:3]
	s_waitcnt vmcnt(13) lgkmcnt(13)
	v_mfma_f32_16x16x32_bf16 v[0:3], v[84:87], v[160:163], v[0:3]
	s_waitcnt vmcnt(12) lgkmcnt(12)
	v_mfma_f32_16x16x32_bf16 v[0:3], v[92:95], v[164:167], v[0:3]
	s_waitcnt vmcnt(11) lgkmcnt(11)
	v_mfma_f32_16x16x32_bf16 v[0:3], v[96:99], v[168:171], v[0:3]
	s_waitcnt vmcnt(10) lgkmcnt(10)
	v_mfma_f32_16x16x32_bf16 v[0:3], v[100:103], v[172:175], v[0:3]
	s_waitcnt vmcnt(9) lgkmcnt(9)
	v_mfma_f32_16x16x32_bf16 v[0:3], v[104:107], v[176:179], v[0:3]
	s_waitcnt vmcnt(8) lgkmcnt(8)
	v_mfma_f32_16x16x32_bf16 v[0:3], v[112:115], v[180:183], v[0:3]
	global_load_dwordx4 v[76:79], v[214:215], off offset:1024
	ds_read_b128 v[152:155], v73 offset:1024
	global_load_dwordx4 v[80:83], v[214:215], off offset:1088
	ds_read_b128 v[156:159], v90 offset:1024
	global_load_dwordx4 v[84:87], v[214:215], off offset:1152
	ds_read_b128 v[160:163], v91 offset:1024
	global_load_dwordx4 v[92:95], v[214:215], off offset:1216
	ds_read_b128 v[164:167], v124 offset:1024
	global_load_dwordx4 v[96:99], v[214:215], off offset:1280
	ds_read_b128 v[168:171], v73 offset:1280
	global_load_dwordx4 v[100:103], v[214:215], off offset:1344
	ds_read_b128 v[172:175], v90 offset:1280
	global_load_dwordx4 v[104:107], v[214:215], off offset:1408
	ds_read_b128 v[176:179], v91 offset:1280
	global_load_dwordx4 v[112:115], v[214:215], off offset:1472
	ds_read_b128 v[180:183], v124 offset:1280
	s_waitcnt vmcnt(15) lgkmcnt(15)
	v_mfma_f32_16x16x32_bf16 v[0:3], v[116:119], v[184:187], v[0:3]
	s_waitcnt vmcnt(14) lgkmcnt(14)
	v_mfma_f32_16x16x32_bf16 v[0:3], v[120:123], v[188:191], v[0:3]
	s_waitcnt vmcnt(13) lgkmcnt(13)
	v_mfma_f32_16x16x32_bf16 v[0:3], v[128:131], v[196:199], v[0:3]
	s_waitcnt vmcnt(12) lgkmcnt(12)
	v_mfma_f32_16x16x32_bf16 v[0:3], v[132:135], v[200:203], v[0:3]
	s_waitcnt vmcnt(11) lgkmcnt(11)
	v_mfma_f32_16x16x32_bf16 v[0:3], v[136:139], v[204:207], v[0:3]
	s_waitcnt vmcnt(10) lgkmcnt(10)
	v_mfma_f32_16x16x32_bf16 v[0:3], v[140:143], v[208:211], v[0:3]
	s_waitcnt vmcnt(9) lgkmcnt(9)
	v_mfma_f32_16x16x32_bf16 v[0:3], v[144:147], v[216:219], v[0:3]
	s_waitcnt vmcnt(8) lgkmcnt(8)
	v_mfma_f32_16x16x32_bf16 v[0:3], v[148:151], v[220:223], v[0:3]
	global_load_dwordx4 v[116:119], v[214:215], off offset:1536
	ds_read_b128 v[184:187], v73 offset:1536
	global_load_dwordx4 v[120:123], v[214:215], off offset:1600
	ds_read_b128 v[188:191], v90 offset:1536
	global_load_dwordx4 v[128:131], v[214:215], off offset:1664
	ds_read_b128 v[196:199], v91 offset:1536
	global_load_dwordx4 v[132:135], v[214:215], off offset:1728
	ds_read_b128 v[200:203], v124 offset:1536
	global_load_dwordx4 v[136:139], v[214:215], off offset:1792
	ds_read_b128 v[204:207], v73 offset:1792
	global_load_dwordx4 v[140:143], v[214:215], off offset:1856
	ds_read_b128 v[208:211], v90 offset:1792
	global_load_dwordx4 v[144:147], v[214:215], off offset:1920
	ds_read_b128 v[216:219], v91 offset:1792
	global_load_dwordx4 v[148:151], v[214:215], off offset:1984
	ds_read_b128 v[220:223], v124 offset:1792
	s_waitcnt vmcnt(15) lgkmcnt(15)
	v_mfma_f32_16x16x32_bf16 v[0:3], v[76:79], v[152:155], v[0:3]
	s_waitcnt vmcnt(14) lgkmcnt(14)
	v_mfma_f32_16x16x32_bf16 v[0:3], v[80:83], v[156:159], v[0:3]
	s_waitcnt vmcnt(13) lgkmcnt(13)
	v_mfma_f32_16x16x32_bf16 v[0:3], v[84:87], v[160:163], v[0:3]
	s_waitcnt vmcnt(12) lgkmcnt(12)
	v_mfma_f32_16x16x32_bf16 v[0:3], v[92:95], v[164:167], v[0:3]
	s_waitcnt vmcnt(11) lgkmcnt(11)
	v_mfma_f32_16x16x32_bf16 v[0:3], v[96:99], v[168:171], v[0:3]
	s_waitcnt vmcnt(10) lgkmcnt(10)
	v_mfma_f32_16x16x32_bf16 v[0:3], v[100:103], v[172:175], v[0:3]
	s_waitcnt vmcnt(9) lgkmcnt(9)
	v_mfma_f32_16x16x32_bf16 v[0:3], v[104:107], v[176:179], v[0:3]
	s_waitcnt vmcnt(8) lgkmcnt(8)
; __device__ __forceinline__ f32x4 mfma32(bf16x8 a, bf16x8 b, f32x4 c) { return __builtin_amdgcn_mfma_f32_16x16x32_bf16(a, b, c, 0, 0, 0); }
; __device__ __forceinline__ void dt_phase(const Ptrs& P, int gw, int NGW, int lane) {
;     ...
;     for (int it = gw; it < MTOK / 16; it += NGW) {
;         const int r0 = 16 * it; f32x4 acc = {0.f, 0.f, 0.f, 0.f};
;         const bf16_t* ap = U + (size_t)(r0 + lc) * DM + 8 * g; const bf16_t* bp = WdtT + (size_t)lc * DM + 8 * g;
; #pragma unroll 8
;         for (int ks = 0; ks < 64; ++ks) { const bf16x8 a = *(const bf16x8*)(ap + ks * 32); const bf16x8 b = *(const bf16x8*)(bp + ks * 32); acc = mfma32(a, b, acc); }
	v_mfma_f32_16x16x32_bf16 v[0:3], v[112:115], v[180:183], v[0:3]
	global_load_dwordx4 v[76:79], v[214:215], off offset:2048
	ds_read_b128 v[152:155], v73 offset:2048
	global_load_dwordx4 v[80:83], v[214:215], off offset:2112
	ds_read_b128 v[156:159], v90 offset:2048
	global_load_dwordx4 v[84:87], v[214:215], off offset:2176
	ds_read_b128 v[160:163], v91 offset:2048
	global_load_dwordx4 v[92:95], v[214:215], off offset:2240
	ds_read_b128 v[164:167], v124 offset:2048
	global_load_dwordx4 v[96:99], v[214:215], off offset:2304
	ds_read_b128 v[168:171], v73 offset:2304
	global_load_dwordx4 v[100:103], v[214:215], off offset:2368
	ds_read_b128 v[172:175], v90 offset:2304
	global_load_dwordx4 v[104:107], v[214:215], off offset:2432
	ds_read_b128 v[176:179], v91 offset:2304
	global_load_dwordx4 v[112:115], v[214:215], off offset:2496
	ds_read_b128 v[180:183], v124 offset:2304
	s_waitcnt vmcnt(15) lgkmcnt(15)
	v_mfma_f32_16x16x32_bf16 v[0:3], v[116:119], v[184:187], v[0:3]
	s_waitcnt vmcnt(14) lgkmcnt(14)
	v_mfma_f32_16x16x32_bf16 v[0:3], v[120:123], v[188:191], v[0:3]
	s_waitcnt vmcnt(13) lgkmcnt(13)
	v_mfma_f32_16x16x32_bf16 v[0:3], v[128:131], v[196:199], v[0:3]
	s_waitcnt vmcnt(12) lgkmcnt(12)
	v_mfma_f32_16x16x32_bf16 v[0:3], v[132:135], v[200:203], v[0:3]
	s_waitcnt vmcnt(11) lgkmcnt(11)
	v_mfma_f32_16x16x32_bf16 v[0:3], v[136:139], v[204:207], v[0:3]
	s_waitcnt vmcnt(10) lgkmcnt(10)
	v_mfma_f32_16x16x32_bf16 v[0:3], v[140:143], v[208:211], v[0:3]
	s_waitcnt vmcnt(9) lgkmcnt(9)
	v_mfma_f32_16x16x32_bf16 v[0:3], v[144:147], v[216:219], v[0:3]
	s_waitcnt vmcnt(8) lgkmcnt(8)
	v_mfma_f32_16x16x32_bf16 v[0:3], v[148:151], v[220:223], v[0:3]
	global_load_dwordx4 v[116:119], v[214:215], off offset:2560
	ds_read_b128 v[184:187], v73 offset:2560
	global_load_dwordx4 v[120:123], v[214:215], off offset:2624
	ds_read_b128 v[188:191], v90 offset:2560
	global_load_dwordx4 v[128:131], v[214:215], off offset:2688
	ds_read_b128 v[196:199], v91 offset:2560
	global_load_dwordx4 v[132:135], v[214:215], off offset:2752
	ds_read_b128 v[200:203], v124 offset:2560
	global_load_dwordx4 v[136:139], v[214:215], off offset:2816
	ds_read_b128 v[204:207], v73 offset:2816
	global_load_dwordx4 v[140:143], v[214:215], off offset:2880
	ds_read_b128 v[208:211], v90 offset:2816
	global_load_dwordx4 v[144:147], v[214:215], off offset:2944
	ds_read_b128 v[216:219], v91 offset:2816
	global_load_dwordx4 v[148:151], v[214:215], off offset:3008
	ds_read_b128 v[220:223], v124 offset:2816
	s_waitcnt vmcnt(15) lgkmcnt(15)
	v_mfma_f32_16x16x32_bf16 v[0:3], v[76:79], v[152:155], v[0:3]
	s_waitcnt vmcnt(14) lgkmcnt(14)
	v_mfma_f32_16x16x32_bf16 v[0:3], v[80:83], v[156:159], v[0:3]
	s_waitcnt vmcnt(13) lgkmcnt(13)
	v_mfma_f32_16x16x32_bf16 v[0:3], v[84:87], v[160:163], v[0:3]
	s_waitcnt vmcnt(12) lgkmcnt(12)
	v_mfma_f32_16x16x32_bf16 v[0:3], v[92:95], v[164:167], v[0:3]
	s_waitcnt vmcnt(11) lgkmcnt(11)
	v_mfma_f32_16x16x32_bf16 v[0:3], v[96:99], v[168:171], v[0:3]
	s_waitcnt vmcnt(10) lgkmcnt(10)
	v_mfma_f32_16x16x32_bf16 v[0:3], v[100:103], v[172:175], v[0:3]
	s_waitcnt vmcnt(9) lgkmcnt(9)
	v_mfma_f32_16x16x32_bf16 v[0:3], v[104:107], v[176:179], v[0:3]
	s_waitcnt vmcnt(8) lgkmcnt(8)
	v_mfma_f32_16x16x32_bf16 v[0:3], v[112:115], v[180:183], v[0:3]
	global_load_dwordx4 v[76:79], v[214:215], off offset:3072
	ds_read_b128 v[152:155], v73 offset:3072
	global_load_dwordx4 v[80:83], v[214:215], off offset:3136
	ds_read_b128 v[156:159], v90 offset:3072
	global_load_dwordx4 v[84:87], v[214:215], off offset:3200
	ds_read_b128 v[160:163], v91 offset:3072
	global_load_dwordx4 v[92:95], v[214:215], off offset:3264
	ds_read_b128 v[164:167], v124 offset:3072
	global_load_dwordx4 v[96:99], v[214:215], off offset:3328
	ds_read_b128 v[168:171], v73 offset:3328
	global_load_dwordx4 v[100:103], v[214:215], off offset:3392
	ds_read_b128 v[172:175], v90 offset:3328
	global_load_dwordx4 v[104:107], v[214:215], off offset:3456
	ds_read_b128 v[176:179], v91 offset:3328
	global_load_dwordx4 v[112:115], v[214:215], off offset:3520
	ds_read_b128 v[180:183], v124 offset:3328
	s_waitcnt vmcnt(15) lgkmcnt(15)
; __device__ __forceinline__ f32x4 mfma32(bf16x8 a, bf16x8 b, f32x4 c) { return __builtin_amdgcn_mfma_f32_16x16x32_bf16(a, b, c, 0, 0, 0); }
; __device__ __forceinline__ void dt_phase(const Ptrs& P, int gw, int NGW, int lane) {
;     ...
;     for (int it = gw; it < MTOK / 16; it += NGW) {
;         const int r0 = 16 * it; f32x4 acc = {0.f, 0.f, 0.f, 0.f};
;         const bf16_t* ap = U + (size_t)(r0 + lc) * DM + 8 * g; const bf16_t* bp = WdtT + (size_t)lc * DM + 8 * g;
; #pragma unroll 8
;         for (int ks = 0; ks < 64; ++ks) { const bf16x8 a = *(const bf16x8*)(ap + ks * 32); const bf16x8 b = *(const bf16x8*)(bp + ks * 32); acc = mfma32(a, b, acc); }
; #pragma unroll
;         for (int r = 0; r < 4; ++r) dtraw[(size_t)(r0 + 4 * g + r) * 16 + lc] = acc[r];
;     }
	v_mfma_f32_16x16x32_bf16 v[0:3], v[116:119], v[184:187], v[0:3]
	s_waitcnt vmcnt(14) lgkmcnt(14)
	v_mfma_f32_16x16x32_bf16 v[0:3], v[120:123], v[188:191], v[0:3]
	s_waitcnt vmcnt(13) lgkmcnt(13)
	v_mfma_f32_16x16x32_bf16 v[0:3], v[128:131], v[196:199], v[0:3]
	s_waitcnt vmcnt(12) lgkmcnt(12)
	v_mfma_f32_16x16x32_bf16 v[0:3], v[132:135], v[200:203], v[0:3]
	s_waitcnt vmcnt(11) lgkmcnt(11)
	v_mfma_f32_16x16x32_bf16 v[0:3], v[136:139], v[204:207], v[0:3]
	s_waitcnt vmcnt(10) lgkmcnt(10)
	v_mfma_f32_16x16x32_bf16 v[0:3], v[140:143], v[208:211], v[0:3]
	s_waitcnt vmcnt(9) lgkmcnt(9)
	v_mfma_f32_16x16x32_bf16 v[0:3], v[144:147], v[216:219], v[0:3]
	s_waitcnt vmcnt(8) lgkmcnt(8)
	v_mfma_f32_16x16x32_bf16 v[0:3], v[148:151], v[220:223], v[0:3]
	global_load_dwordx4 v[116:119], v[214:215], off offset:3584
	ds_read_b128 v[184:187], v73 offset:3584
	global_load_dwordx4 v[120:123], v[214:215], off offset:3648
	ds_read_b128 v[188:191], v90 offset:3584
	global_load_dwordx4 v[128:131], v[214:215], off offset:3712
	ds_read_b128 v[196:199], v91 offset:3584
	global_load_dwordx4 v[132:135], v[214:215], off offset:3776
	ds_read_b128 v[200:203], v124 offset:3584
	global_load_dwordx4 v[136:139], v[214:215], off offset:3840
	ds_read_b128 v[204:207], v73 offset:3840
	global_load_dwordx4 v[140:143], v[214:215], off offset:3904
	ds_read_b128 v[208:211], v90 offset:3840
	global_load_dwordx4 v[144:147], v[214:215], off offset:3968
	ds_read_b128 v[216:219], v91 offset:3840
	global_load_dwordx4 v[148:151], v[214:215], off offset:4032
	ds_read_b128 v[220:223], v124 offset:3840
	s_waitcnt vmcnt(15) lgkmcnt(15)
	v_mfma_f32_16x16x32_bf16 v[0:3], v[76:79], v[152:155], v[0:3]
	s_waitcnt vmcnt(14) lgkmcnt(14)
	v_mfma_f32_16x16x32_bf16 v[0:3], v[80:83], v[156:159], v[0:3]
	s_waitcnt vmcnt(13) lgkmcnt(13)
	v_mfma_f32_16x16x32_bf16 v[0:3], v[84:87], v[160:163], v[0:3]
	s_waitcnt vmcnt(12) lgkmcnt(12)
	v_mfma_f32_16x16x32_bf16 v[0:3], v[92:95], v[164:167], v[0:3]
	s_waitcnt vmcnt(11) lgkmcnt(11)
	v_mfma_f32_16x16x32_bf16 v[0:3], v[96:99], v[168:171], v[0:3]
	s_waitcnt vmcnt(10) lgkmcnt(10)
	v_mfma_f32_16x16x32_bf16 v[0:3], v[100:103], v[172:175], v[0:3]
	s_waitcnt vmcnt(9) lgkmcnt(9)
	v_mfma_f32_16x16x32_bf16 v[0:3], v[104:107], v[176:179], v[0:3]
	s_waitcnt vmcnt(8) lgkmcnt(8)
	v_mfma_f32_16x16x32_bf16 v[0:3], v[112:115], v[180:183], v[0:3]
	s_waitcnt vmcnt(7) lgkmcnt(7)
	v_mfma_f32_16x16x32_bf16 v[0:3], v[116:119], v[184:187], v[0:3]
	s_waitcnt vmcnt(6) lgkmcnt(6)
	v_mfma_f32_16x16x32_bf16 v[0:3], v[120:123], v[188:191], v[0:3]
	s_waitcnt vmcnt(5) lgkmcnt(5)
	v_mfma_f32_16x16x32_bf16 v[0:3], v[128:131], v[196:199], v[0:3]
	s_waitcnt vmcnt(4) lgkmcnt(4)
	v_mfma_f32_16x16x32_bf16 v[0:3], v[132:135], v[200:203], v[0:3]
	s_waitcnt vmcnt(3) lgkmcnt(3)
	v_mfma_f32_16x16x32_bf16 v[0:3], v[136:139], v[204:207], v[0:3]
	s_waitcnt vmcnt(2) lgkmcnt(2)
	v_mfma_f32_16x16x32_bf16 v[0:3], v[140:143], v[208:211], v[0:3]
	s_waitcnt vmcnt(1) lgkmcnt(1)
	v_mfma_f32_16x16x32_bf16 v[0:3], v[144:147], v[216:219], v[0:3]
	s_waitcnt vmcnt(0) lgkmcnt(0)
	v_mfma_f32_16x16x32_bf16 v[0:3], v[148:151], v[220:223], v[0:3]
	s_nop 7
	v_lshl_or_b32 v12, v14, 4, v15
	v_ashrrev_i32_e32 v13, 31, v12
	v_lshlrev_b64 v[18:19], 6, v[12:13]
	v_lshl_add_u64 v[18:19], v[10:11], 0, v[18:19]
	s_nop 2
	global_store_dword v[18:19], v0, off
	v_or_b32_e32 v18, 1, v12
	v_ashrrev_i32_e32 v19, 31, v18
	v_lshlrev_b64 v[18:19], 6, v[18:19]
	v_lshl_add_u64 v[18:19], v[10:11], 0, v[18:19]
	v_or_b32_e32 v0, 2, v12
	global_store_dword v[18:19], v1, off
	v_ashrrev_i32_e32 v1, 31, v0
	v_lshlrev_b64 v[0:1], 6, v[0:1]
	v_lshl_add_u64 v[0:1], v[10:11], 0, v[0:1]
	global_store_dword v[0:1], v2, off
	v_or_b32_e32 v0, 3, v12
	v_ashrrev_i32_e32 v1, 31, v0
	v_lshlrev_b64 v[0:1], 6, v[0:1]
	v_lshl_add_u64 v[0:1], v[10:11], 0, v[0:1]
	global_store_dword v[0:1], v3, off
	v_add_u32_e32 v0, 0x800, v14
	v_cmp_lt_i32_e32 vcc, 1, v14
	v_add_u32_e32 v4, 0x8000, v4
	s_or_b64 s[6:7], vcc, s[6:7]
	v_mov_b32_e32 v14, v0
	s_andn2_b64 exec, exec, s[6:7]
	s_cbranch_execnz .LBB0_232
	s_or_b64 exec, exec, s[6:7]
